# phase 0 converter: chunk numbers interleaved across the eight counters so that all workgroups sweep the same region of a matrix
# speedup vs baseline: 1.0062x; 1.0062x over previous
.LBB0_1374:
	s_mov_b64 s[60:61], s[90:91]
	v_readlane_b32 s67, v235, 23
	v_readlane_b32 s66, v235, 24
	v_and_b32_e32 v102, 63, v170
	v_and_b32_e32 v99, 7, v102
	v_lshlrev_b32_e32 v96, 3, v99
	v_lshlrev_b32_e32 v99, 4, v99
	v_lshrrev_b32_e32 v98, 3, v102
	v_lshlrev_b32_e32 v97, 4, v98
	v_lshlrev_b32_e32 v98, 2, v98
	v_lshrrev_b32_e32 v102, 6, v170
	s_nop 0
	v_readfirstlane_b32 s6, v102
	v_readlane_b32 s4, v235, 34
	v_readlane_b32 s5, v235, 35
	s_mov_b64 s[34:35], exec
	s_mov_b64 exec, 1
	v_readlane_b32 s17, v237, 0
	s_and_b32 s17, s17, 7
	s_lshl_b32 s17, s17, 8
	s_add_u32 s17, s17, 0x40e0
	v_mov_b32_e32 v104, s17
	v_mov_b32_e32 v105, 1
	s_nop 1
	global_atomic_add v103, v104, v105, s[4:5] sc0
	s_mov_b64 exec, s[34:35]
	s_waitcnt vmcnt(0)
	v_readfirstlane_b32 s6, v103
	s_cmp_ge_u32 s6, 1336
	s_cbranch_scc1 .Lcv_done
	v_readlane_b32 s17, v237, 0
	s_and_b32 s17, s17, 7
	s_lshl_b32 s6, s6, 3
	s_add_u32 s6, s6, s17
	s_lshl_b32 s6, s6, 2
	s_mov_b32 s41, 0
	s_cmp_ge_u32 s6, 22528
	s_cbranch_scc1 .Lcv_t1_1
	s_mul_hi_u32 s4, s6, 1525202
	s_mul_i32 s5, s4, 2816
	s_sub_u32 s17, s6, s5
	s_mul_hi_u32 s34, s17, 24403224
	s_mul_i32 s5, s34, 176
	s_sub_u32 s35, s17, s5
	s_lshl_b32 s40, s35, 5
	s_cmp_ge_u32 s40, 2816
	s_cselect_b32 s5, 1, 0
	s_mul_i32 s17, s5, 2816
	s_sub_u32 s40, s40, s17
	s_lshl_b32 s5, s5, 5
	s_lshr_b32 s17, s40, 6
	s_lshl_b32 s17, s17, 7
	s_add_u32 s5, s5, s17
	s_bfe_u32 s17, s40, 0x10005
	s_lshl_b32 s17, s17, 6
	s_add_u32 s40, s5, s17
	v_readlane_b32 s8, v237, 29
	v_readlane_b32 s9, v237, 30
	s_mul_i32 s5, s4, 0x1600000
	s_mul_i32 s17, s34, 0x160000
	s_add_u32 s5, s5, s17
	s_lshl_b32 s17, s35, 7
	s_add_u32 s5, s5, s17
	s_add_u32 s8, s8, s5
	s_addc_u32 s9, s9, 0
	s_movk_i32 s16, 0x5800
	v_readlane_b32 s10, v235, 34
	v_readlane_b32 s11, v235, 35
	s_mul_i32 s5, s4, 0xbb0000
	s_mul_i32 s17, s40, 0x880
	s_add_u32 s5, s5, s17
	s_lshl_b32 s17, s34, 7
	s_add_u32 s5, s5, s17
	s_add_u32 s5, s5, 0x8000
	s_add_u32 s10, s10, s5
	s_addc_u32 s11, s11, 0
	s_lshl_b32 s41, s41, 31
	s_or_b32 s12, s41, 0x880
	s_branch .Lcv_dec1

.Lcv_chunkend_a:
	v_readfirstlane_b32 s18, v103
	s_cmp_lt_u32 s18, 1336
	s_cbranch_scc0 .Lcv_nonext_a
	v_readlane_b32 s17, v237, 0
	s_and_b32 s17, s17, 7
	s_lshl_b32 s18, s18, 3
	s_add_u32 s18, s18, s17
	s_lshl_b32 s18, s18, 2
